# epilogue row-scale partial sums staged into LDS by DMA during the K-loop (FFN-up, proj0, proj1) on top of the hand-scheduled mLSTM loop version
# speedup vs baseline: 1.0053x; 1.0053x over previous
.LBB0_82:
	s_ashr_i32 s27, s26, 31
	v_mov_b64_e32 v[2:3], 0xb00
	s_lshl_b64 s[22:23], s[26:27], 19
	v_cmp_lt_i64_e32 vcc, s[36:37], v[2:3]
	s_add_u32 s36, s96, s22
	s_addc_u32 s37, s97, s23
	s_and_b64 s[22:23], vcc, exec
	s_cselect_b32 s27, s37, s29
	s_cselect_b32 s56, s36, s28
	s_ashr_i32 s7, s6, 31
	s_lshl_b64 s[22:23], s[6:7], 19
	s_add_u32 s44, s4, s22
	s_addc_u32 s45, s16, s23
	s_and_b64 s[22:23], vcc, exec
	s_cselect_b32 s7, s45, s31
	s_cselect_b32 s57, s44, s30
	s_add_u32 s28, s28, 0x40080
	s_addc_u32 s29, s29, 0
	s_add_u32 s58, s30, 0x100
	s_addc_u32 s59, s31, 0
	s_mov_b32 s60, -2
	s_lshl_b32 s98, s55, 14
	s_add_u32 s98, s100, s98
	s_addc_u32 s99, s101, 0
	s_mov_b64 vcc, -1
	s_cmpk_gt_u32 s0, 0xff
	s_cbranch_scc0 .Lrs_i2_pre
	s_barrier
.Lrs_i2_pre:
	s_add_u32 s1, s28, 0xfffc0080
	s_addc_u32 s22, s29, -1
	s_add_i32 s23, 0, 0x10000
	v_add_u32_e32 v142, s23, v201
	ds_read_b128 v[130:133], v142
	ds_read_b128 v[134:137], v142 offset:1024
	ds_read_b128 v[138:141], v142 offset:2048
	ds_read_b128 v[142:145], v142 offset:3072
	s_cmp_eq_u32 s60, 12
	s_cselect_b32 s43, s27, s22
	s_cselect_b32 s42, s56, s1
	s_cselect_b32 s31, s7, s59
	s_cselect_b32 s30, s57, s58
	v_lshl_add_u64 v[176:177], s[28:29], 0, v[178:179]
	s_add_i32 m0, s46, 0xc000
	ds_read_b128 v[146:149], v205
	ds_read_b128 v[150:153], v205 offset:1024
	ds_read_b128 v[182:185], v205 offset:2048
	ds_read_b128 v[186:189], v205 offset:3072
	ds_read_b128 v[190:193], v205 offset:4096
	ds_read_b128 v[194:197], v205 offset:5120
	ds_read_b128 v[206:209], v205 offset:6144
	ds_read_b128 v[216:219], v205 offset:7168
	global_load_lds_dwordx4 v[176:177], off
	v_lshl_add_u64 v[176:177], s[28:29], 0, v[180:181]
	s_add_i32 m0, s46, 0xe000
	s_nop 0
	global_load_lds_dwordx4 v[176:177], off
	s_add_i32 s1, 0, 0x14000
	v_add_u32_e32 v168, s1, v201
	ds_read_b128 v[230:233], v168
	ds_read_b128 v[234:237], v168 offset:1024
	ds_read_b128 v[238:241], v168 offset:2048
	ds_read_b128 v[242:245], v168 offset:3072
	s_waitcnt vmcnt(8)
	s_waitcnt lgkmcnt(0)
	s_barrier
	s_setprio 1
	v_mfma_f32_16x16x32_bf16 v[126:129], v[130:133], v[146:149], 0
	v_mfma_f32_16x16x32_bf16 v[118:121], v[138:141], v[146:149], 0
	v_mfma_f32_16x16x32_bf16 v[110:113], v[130:133], v[182:185], 0
	v_mfma_f32_16x16x32_bf16 v[102:105], v[138:141], v[182:185], 0
	v_mfma_f32_16x16x32_bf16 v[94:97], v[130:133], v[190:193], 0
	v_mfma_f32_16x16x32_bf16 v[86:89], v[138:141], v[190:193], 0
	v_mfma_f32_16x16x32_bf16 v[78:81], v[130:133], v[206:209], 0
	v_mfma_f32_16x16x32_bf16 v[70:73], v[138:141], v[206:209], 0
	v_mfma_f32_16x16x32_bf16 v[126:129], v[134:137], v[150:153], v[126:129]
	v_mfma_f32_16x16x32_bf16 v[118:121], v[142:145], v[150:153], v[118:121]
	v_mfma_f32_16x16x32_bf16 v[110:113], v[134:137], v[186:189], v[110:113]
	v_mfma_f32_16x16x32_bf16 v[102:105], v[142:145], v[186:189], v[102:105]
	v_mfma_f32_16x16x32_bf16 v[94:97], v[134:137], v[194:197], v[94:97]
	v_mfma_f32_16x16x32_bf16 v[86:89], v[142:145], v[194:197], v[86:89]
	v_mfma_f32_16x16x32_bf16 v[78:81], v[134:137], v[216:219], v[78:81]
	v_mfma_f32_16x16x32_bf16 v[70:73], v[142:145], v[216:219], v[70:73]
	v_mfma_f32_16x16x32_bf16 v[122:125], v[230:233], v[146:149], 0
	v_mfma_f32_16x16x32_bf16 v[114:117], v[238:241], v[146:149], 0
	v_mfma_f32_16x16x32_bf16 v[106:109], v[230:233], v[182:185], 0
	v_mfma_f32_16x16x32_bf16 v[98:101], v[238:241], v[182:185], 0
	v_mfma_f32_16x16x32_bf16 v[90:93], v[230:233], v[190:193], 0
	v_mfma_f32_16x16x32_bf16 v[82:85], v[238:241], v[190:193], 0
	v_mfma_f32_16x16x32_bf16 v[74:77], v[230:233], v[206:209], 0
	v_mfma_f32_16x16x32_bf16 v[66:69], v[238:241], v[206:209], 0
	v_mfma_f32_16x16x32_bf16 v[122:125], v[234:237], v[150:153], v[122:125]
	v_mfma_f32_16x16x32_bf16 v[114:117], v[242:245], v[150:153], v[114:117]
	v_mfma_f32_16x16x32_bf16 v[106:109], v[234:237], v[186:189], v[106:109]
	v_mfma_f32_16x16x32_bf16 v[98:101], v[242:245], v[186:189], v[98:101]
	v_mfma_f32_16x16x32_bf16 v[90:93], v[234:237], v[194:197], v[90:93]
	v_mfma_f32_16x16x32_bf16 v[82:85], v[242:245], v[194:197], v[82:85]
	v_mfma_f32_16x16x32_bf16 v[74:77], v[234:237], v[216:219], v[74:77]
	v_mfma_f32_16x16x32_bf16 v[66:69], v[242:245], v[216:219], v[66:69]
	s_setprio 0
	s_barrier
	ds_read_b128 v[146:149], v205 offset:16384
	ds_read_b128 v[150:153], v205 offset:17408
	ds_read_b128 v[182:185], v205 offset:18432
	ds_read_b128 v[186:189], v205 offset:19456
	ds_read_b128 v[190:193], v205 offset:20480
	ds_read_b128 v[194:197], v205 offset:21504
	ds_read_b128 v[206:209], v205 offset:22528
	ds_read_b128 v[216:219], v205 offset:23552
	s_cbranch_vccz .Lss_i2
	v_lshlrev_b32_e32 v176, 4, v167
	s_lshl_b32 m0, s46, 1
	v_add_u32_e32 v176, s46, v176
	s_add_i32 m0, m0, 0x20000
	s_mov_b64 vcc, 0
	global_load_lds_dwordx4 v176, s[98:99]
	global_load_lds_dwordx4 v176, s[98:99] offset:1024
	s_add_i32 s22, s23, s17
	v_lshl_add_u64 v[176:177], s[30:31], 0, v[0:1]
	s_mov_b32 m0, s22
	s_nop 0
	global_load_lds_dwordx4 v[176:177], off
	v_lshl_add_u64 v[202:203], s[30:31], 0, v[154:155]
	s_add_i32 m0, s22, 0x2000
	s_nop 0
	global_load_lds_dwordx4 v[202:203], off
	s_mov_b32 m0, s46
	v_lshl_add_u64 v[220:221], s[42:43], 0, v[158:159]
	global_load_lds_dwordx4 v[220:221], off
	v_lshl_add_u64 v[246:247], s[42:43], 0, v[156:157]
	s_mov_b32 m0, s47
	s_nop 0
	global_load_lds_dwordx4 v[246:247], off
	s_add_u32 s22, s30, 0x40000
	s_addc_u32 s23, s31, 0
	s_add_i32 s1, s1, s17
	s_mov_b32 m0, s1
	s_nop 0
	global_load_lds_dwordx4 v0, s[22:23]
	s_add_i32 m0, s1, 0x2000
	s_nop 0
	global_load_lds_dwordx4 v154, s[22:23]
	s_waitcnt vmcnt(8)
	s_waitcnt lgkmcnt(0)
	s_barrier
	s_setprio 1
	v_mfma_f32_16x16x32_bf16 v[62:65], v[130:133], v[146:149], 0
	v_mfma_f32_16x16x32_bf16 v[54:57], v[138:141], v[146:149], 0
	v_mfma_f32_16x16x32_bf16 v[46:49], v[130:133], v[182:185], 0
	v_mfma_f32_16x16x32_bf16 v[38:41], v[138:141], v[182:185], 0
	v_mfma_f32_16x16x32_bf16 v[30:33], v[130:133], v[190:193], 0
	v_mfma_f32_16x16x32_bf16 v[22:25], v[138:141], v[190:193], 0
	v_mfma_f32_16x16x32_bf16 v[14:17], v[130:133], v[206:209], 0
	v_mfma_f32_16x16x32_bf16 v[6:9], v[138:141], v[206:209], 0
	v_mfma_f32_16x16x32_bf16 v[62:65], v[134:137], v[150:153], v[62:65]
	v_mfma_f32_16x16x32_bf16 v[54:57], v[142:145], v[150:153], v[54:57]
	v_mfma_f32_16x16x32_bf16 v[46:49], v[134:137], v[186:189], v[46:49]
	v_mfma_f32_16x16x32_bf16 v[38:41], v[142:145], v[186:189], v[38:41]
	v_mfma_f32_16x16x32_bf16 v[30:33], v[134:137], v[194:197], v[30:33]
	v_mfma_f32_16x16x32_bf16 v[22:25], v[142:145], v[194:197], v[22:25]
	v_mfma_f32_16x16x32_bf16 v[14:17], v[134:137], v[216:219], v[14:17]
	v_mfma_f32_16x16x32_bf16 v[6:9], v[142:145], v[216:219], v[6:9]
	v_mfma_f32_16x16x32_bf16 v[58:61], v[230:233], v[146:149], 0
	v_mfma_f32_16x16x32_bf16 v[50:53], v[238:241], v[146:149], 0
	v_mfma_f32_16x16x32_bf16 v[42:45], v[230:233], v[182:185], 0
	v_mfma_f32_16x16x32_bf16 v[34:37], v[238:241], v[182:185], 0
	v_mfma_f32_16x16x32_bf16 v[26:29], v[230:233], v[190:193], 0
	v_mfma_f32_16x16x32_bf16 v[18:21], v[238:241], v[190:193], 0
	v_mfma_f32_16x16x32_bf16 v[10:13], v[230:233], v[206:209], 0
	v_mfma_f32_16x16x32_bf16 v[2:5], v[238:241], v[206:209], 0
	v_mfma_f32_16x16x32_bf16 v[58:61], v[234:237], v[150:153], v[58:61]
	v_mfma_f32_16x16x32_bf16 v[50:53], v[242:245], v[150:153], v[50:53]
	v_mfma_f32_16x16x32_bf16 v[42:45], v[234:237], v[186:189], v[42:45]
	v_mfma_f32_16x16x32_bf16 v[34:37], v[242:245], v[186:189], v[34:37]
	v_mfma_f32_16x16x32_bf16 v[26:29], v[234:237], v[194:197], v[26:29]
	v_mfma_f32_16x16x32_bf16 v[18:21], v[242:245], v[194:197], v[18:21]
	v_mfma_f32_16x16x32_bf16 v[10:13], v[234:237], v[216:219], v[10:13]
	v_mfma_f32_16x16x32_bf16 v[2:5], v[242:245], v[216:219], v[2:5]
	s_setprio 0
	s_barrier
	s_add_i32 s1, 0, 0x18000
	v_add_u32_e32 v142, s1, v201
	ds_read_b128 v[130:133], v142
	ds_read_b128 v[134:137], v142 offset:1024
	ds_read_b128 v[138:141], v142 offset:2048
	ds_read_b128 v[142:145], v142 offset:3072
	s_add_u32 s22, s42, 0x40000
	s_addc_u32 s23, s43, 0
	s_mov_b32 m0, s48
	v_lshl_add_u64 v[230:231], s[22:23], 0, v[158:159]
	ds_read_b128 v[146:149], v205 offset:32768
	ds_read_b128 v[150:153], v205 offset:33792
	ds_read_b128 v[182:185], v205 offset:34816
	ds_read_b128 v[186:189], v205 offset:35840
	ds_read_b128 v[190:193], v205 offset:36864
	ds_read_b128 v[194:197], v205 offset:37888
	ds_read_b128 v[206:209], v205 offset:38912
	ds_read_b128 v[216:219], v205 offset:39936
	global_load_lds_dwordx4 v[230:231], off
	v_lshl_add_u64 v[230:231], s[22:23], 0, v[156:157]
	s_mov_b32 m0, s49
	s_nop 0
	global_load_lds_dwordx4 v[230:231], off
	s_add_i32 s33, 0, 0x1c000
	v_add_u32_e32 v168, s33, v201
	ds_read_b128 v[230:233], v168
	ds_read_b128 v[234:237], v168 offset:1024
	ds_read_b128 v[238:241], v168 offset:2048
	ds_read_b128 v[242:245], v168 offset:3072
	s_waitcnt vmcnt(8)
	s_waitcnt lgkmcnt(0)
	s_barrier
	s_setprio 1
	v_mfma_f32_16x16x32_bf16 v[126:129], v[130:133], v[146:149], v[126:129]
	v_mfma_f32_16x16x32_bf16 v[118:121], v[138:141], v[146:149], v[118:121]
	v_mfma_f32_16x16x32_bf16 v[110:113], v[130:133], v[182:185], v[110:113]
	v_mfma_f32_16x16x32_bf16 v[102:105], v[138:141], v[182:185], v[102:105]
	v_mfma_f32_16x16x32_bf16 v[94:97], v[130:133], v[190:193], v[94:97]
	v_mfma_f32_16x16x32_bf16 v[86:89], v[138:141], v[190:193], v[86:89]
	v_mfma_f32_16x16x32_bf16 v[78:81], v[130:133], v[206:209], v[78:81]
	v_mfma_f32_16x16x32_bf16 v[70:73], v[138:141], v[206:209], v[70:73]
	v_mfma_f32_16x16x32_bf16 v[126:129], v[134:137], v[150:153], v[126:129]
	v_mfma_f32_16x16x32_bf16 v[118:121], v[142:145], v[150:153], v[118:121]
	v_mfma_f32_16x16x32_bf16 v[110:113], v[134:137], v[186:189], v[110:113]
	v_mfma_f32_16x16x32_bf16 v[102:105], v[142:145], v[186:189], v[102:105]
	v_mfma_f32_16x16x32_bf16 v[94:97], v[134:137], v[194:197], v[94:97]
	v_mfma_f32_16x16x32_bf16 v[86:89], v[142:145], v[194:197], v[86:89]
	v_mfma_f32_16x16x32_bf16 v[78:81], v[134:137], v[216:219], v[78:81]
	v_mfma_f32_16x16x32_bf16 v[70:73], v[142:145], v[216:219], v[70:73]
	v_mfma_f32_16x16x32_bf16 v[122:125], v[230:233], v[146:149], v[122:125]
	v_mfma_f32_16x16x32_bf16 v[114:117], v[238:241], v[146:149], v[114:117]
	v_mfma_f32_16x16x32_bf16 v[106:109], v[230:233], v[182:185], v[106:109]
	v_mfma_f32_16x16x32_bf16 v[98:101], v[238:241], v[182:185], v[98:101]
	v_mfma_f32_16x16x32_bf16 v[90:93], v[230:233], v[190:193], v[90:93]
	v_mfma_f32_16x16x32_bf16 v[82:85], v[238:241], v[190:193], v[82:85]
	v_mfma_f32_16x16x32_bf16 v[74:77], v[230:233], v[206:209], v[74:77]
	v_mfma_f32_16x16x32_bf16 v[66:69], v[238:241], v[206:209], v[66:69]
	v_mfma_f32_16x16x32_bf16 v[122:125], v[234:237], v[150:153], v[122:125]
	v_mfma_f32_16x16x32_bf16 v[114:117], v[242:245], v[150:153], v[114:117]
	v_mfma_f32_16x16x32_bf16 v[106:109], v[234:237], v[186:189], v[106:109]
	v_mfma_f32_16x16x32_bf16 v[98:101], v[242:245], v[186:189], v[98:101]
	v_mfma_f32_16x16x32_bf16 v[90:93], v[234:237], v[194:197], v[90:93]
	v_mfma_f32_16x16x32_bf16 v[82:85], v[242:245], v[194:197], v[82:85]
	v_mfma_f32_16x16x32_bf16 v[74:77], v[234:237], v[216:219], v[74:77]
	v_mfma_f32_16x16x32_bf16 v[66:69], v[242:245], v[216:219], v[66:69]
	s_setprio 0
	s_barrier
	ds_read_b128 v[146:149], v205 offset:49152
	ds_read_b128 v[150:153], v205 offset:50176
	ds_read_b128 v[182:185], v205 offset:51200
	ds_read_b128 v[186:189], v205 offset:52224
	ds_read_b128 v[190:193], v205 offset:53248
	ds_read_b128 v[194:197], v205 offset:54272
	ds_read_b128 v[206:209], v205 offset:55296
	ds_read_b128 v[216:219], v205 offset:56320
	s_add_i32 s1, s1, s17
	v_lshl_add_u64 v[176:177], v[176:177], 0, s[12:13]
	s_mov_b32 m0, s1
	s_nop 0
	global_load_lds_dwordx4 v[176:177], off
	v_lshl_add_u64 v[176:177], v[202:203], 0, s[12:13]
	s_add_i32 m0, s1, 0x2000
	s_nop 0
	global_load_lds_dwordx4 v[176:177], off
	s_mov_b32 m0, s20
	v_lshl_add_u64 v[176:177], v[220:221], 0, s[12:13]
	global_load_lds_dwordx4 v[176:177], off
	v_lshl_add_u64 v[176:177], v[246:247], 0, s[12:13]
	s_mov_b32 m0, s21
	s_nop 0
	global_load_lds_dwordx4 v[176:177], off
	s_add_u32 s22, s30, 0x40080
	s_addc_u32 s23, s31, 0
	s_add_i32 s1, s33, s17
	s_mov_b32 m0, s1
	s_nop 0
	global_load_lds_dwordx4 v0, s[22:23]
	s_add_i32 m0, s1, 0x2000
	s_nop 0
	global_load_lds_dwordx4 v154, s[22:23]
	s_waitcnt vmcnt(8)
	s_waitcnt lgkmcnt(0)
	s_barrier
	s_setprio 1
	v_mfma_f32_16x16x32_bf16 v[62:65], v[130:133], v[146:149], v[62:65]
	v_mfma_f32_16x16x32_bf16 v[54:57], v[138:141], v[146:149], v[54:57]
	v_mfma_f32_16x16x32_bf16 v[46:49], v[130:133], v[182:185], v[46:49]
	v_mfma_f32_16x16x32_bf16 v[38:41], v[138:141], v[182:185], v[38:41]
	v_mfma_f32_16x16x32_bf16 v[30:33], v[130:133], v[190:193], v[30:33]
	v_mfma_f32_16x16x32_bf16 v[22:25], v[138:141], v[190:193], v[22:25]
	v_mfma_f32_16x16x32_bf16 v[14:17], v[130:133], v[206:209], v[14:17]
	v_mfma_f32_16x16x32_bf16 v[6:9], v[138:141], v[206:209], v[6:9]
	v_mfma_f32_16x16x32_bf16 v[62:65], v[134:137], v[150:153], v[62:65]
	v_mfma_f32_16x16x32_bf16 v[54:57], v[142:145], v[150:153], v[54:57]
	v_mfma_f32_16x16x32_bf16 v[46:49], v[134:137], v[186:189], v[46:49]
	v_mfma_f32_16x16x32_bf16 v[38:41], v[142:145], v[186:189], v[38:41]
	v_mfma_f32_16x16x32_bf16 v[30:33], v[134:137], v[194:197], v[30:33]
	v_mfma_f32_16x16x32_bf16 v[22:25], v[142:145], v[194:197], v[22:25]
	v_mfma_f32_16x16x32_bf16 v[14:17], v[134:137], v[216:219], v[14:17]
	v_mfma_f32_16x16x32_bf16 v[6:9], v[142:145], v[216:219], v[6:9]
	v_mfma_f32_16x16x32_bf16 v[58:61], v[230:233], v[146:149], v[58:61]
	v_mfma_f32_16x16x32_bf16 v[50:53], v[238:241], v[146:149], v[50:53]
	v_mfma_f32_16x16x32_bf16 v[42:45], v[230:233], v[182:185], v[42:45]
	v_mfma_f32_16x16x32_bf16 v[34:37], v[238:241], v[182:185], v[34:37]
	v_mfma_f32_16x16x32_bf16 v[26:29], v[230:233], v[190:193], v[26:29]
	v_mfma_f32_16x16x32_bf16 v[18:21], v[238:241], v[190:193], v[18:21]
	v_mfma_f32_16x16x32_bf16 v[10:13], v[230:233], v[206:209], v[10:13]
	v_mfma_f32_16x16x32_bf16 v[2:5], v[238:241], v[206:209], v[2:5]
	v_mfma_f32_16x16x32_bf16 v[58:61], v[234:237], v[150:153], v[58:61]
	v_mfma_f32_16x16x32_bf16 v[50:53], v[242:245], v[150:153], v[50:53]
	v_mfma_f32_16x16x32_bf16 v[42:45], v[234:237], v[186:189], v[42:45]
	v_mfma_f32_16x16x32_bf16 v[34:37], v[242:245], v[186:189], v[34:37]
	v_mfma_f32_16x16x32_bf16 v[26:29], v[234:237], v[194:197], v[26:29]
	v_mfma_f32_16x16x32_bf16 v[18:21], v[242:245], v[194:197], v[18:21]
	v_mfma_f32_16x16x32_bf16 v[10:13], v[234:237], v[216:219], v[10:13]
	v_mfma_f32_16x16x32_bf16 v[2:5], v[242:245], v[216:219], v[2:5]
	s_setprio 0
	s_add_i32 s60, s60, 2
	s_add_u32 s28, s28, 0x100
	s_addc_u32 s29, s29, 0
	s_add_u32 s58, s58, 0x100
	s_addc_u32 s59, s59, 0
	s_cmp_gt_u32 s60, 13
	s_barrier
.LBB0_83:
	s_add_u32 s1, s28, 0xfffc0080
	s_addc_u32 s22, s29, -1
	s_add_i32 s23, 0, 0x10000
	v_add_u32_e32 v142, s23, v201
	ds_read_b128 v[130:133], v142
	ds_read_b128 v[134:137], v142 offset:1024
	ds_read_b128 v[138:141], v142 offset:2048
	ds_read_b128 v[142:145], v142 offset:3072
	s_cmp_eq_u32 s60, 12
	s_cselect_b32 s43, s27, s22
	s_cselect_b32 s42, s56, s1
	s_cselect_b32 s31, s7, s59
	s_cselect_b32 s30, s57, s58
	v_lshl_add_u64 v[176:177], s[28:29], 0, v[178:179]
	s_add_i32 m0, s46, 0xc000
	ds_read_b128 v[146:149], v205
	ds_read_b128 v[150:153], v205 offset:1024
	ds_read_b128 v[182:185], v205 offset:2048
	ds_read_b128 v[186:189], v205 offset:3072
	ds_read_b128 v[190:193], v205 offset:4096
	ds_read_b128 v[194:197], v205 offset:5120
	ds_read_b128 v[206:209], v205 offset:6144
	ds_read_b128 v[216:219], v205 offset:7168
	global_load_lds_dwordx4 v[176:177], off
	v_lshl_add_u64 v[176:177], s[28:29], 0, v[180:181]
	s_add_i32 m0, s46, 0xe000
	s_nop 0
	global_load_lds_dwordx4 v[176:177], off
	s_add_i32 s1, 0, 0x14000
	v_add_u32_e32 v168, s1, v201
	ds_read_b128 v[230:233], v168
	ds_read_b128 v[234:237], v168 offset:1024
	ds_read_b128 v[238:241], v168 offset:2048
	ds_read_b128 v[242:245], v168 offset:3072
	s_waitcnt vmcnt(8)
	s_waitcnt lgkmcnt(0)
	s_barrier
	s_setprio 1
	v_mfma_f32_16x16x32_bf16 v[126:129], v[130:133], v[146:149], v[126:129]
	v_mfma_f32_16x16x32_bf16 v[118:121], v[138:141], v[146:149], v[118:121]
	v_mfma_f32_16x16x32_bf16 v[110:113], v[130:133], v[182:185], v[110:113]
	v_mfma_f32_16x16x32_bf16 v[102:105], v[138:141], v[182:185], v[102:105]
	v_mfma_f32_16x16x32_bf16 v[94:97], v[130:133], v[190:193], v[94:97]
	v_mfma_f32_16x16x32_bf16 v[86:89], v[138:141], v[190:193], v[86:89]
	v_mfma_f32_16x16x32_bf16 v[78:81], v[130:133], v[206:209], v[78:81]
	v_mfma_f32_16x16x32_bf16 v[70:73], v[138:141], v[206:209], v[70:73]
	v_mfma_f32_16x16x32_bf16 v[126:129], v[134:137], v[150:153], v[126:129]
	v_mfma_f32_16x16x32_bf16 v[118:121], v[142:145], v[150:153], v[118:121]
	v_mfma_f32_16x16x32_bf16 v[110:113], v[134:137], v[186:189], v[110:113]
	v_mfma_f32_16x16x32_bf16 v[102:105], v[142:145], v[186:189], v[102:105]
	v_mfma_f32_16x16x32_bf16 v[94:97], v[134:137], v[194:197], v[94:97]
	v_mfma_f32_16x16x32_bf16 v[86:89], v[142:145], v[194:197], v[86:89]
	v_mfma_f32_16x16x32_bf16 v[78:81], v[134:137], v[216:219], v[78:81]
	v_mfma_f32_16x16x32_bf16 v[70:73], v[142:145], v[216:219], v[70:73]
	v_mfma_f32_16x16x32_bf16 v[122:125], v[230:233], v[146:149], v[122:125]
	v_mfma_f32_16x16x32_bf16 v[114:117], v[238:241], v[146:149], v[114:117]
	v_mfma_f32_16x16x32_bf16 v[106:109], v[230:233], v[182:185], v[106:109]
	v_mfma_f32_16x16x32_bf16 v[98:101], v[238:241], v[182:185], v[98:101]
	v_mfma_f32_16x16x32_bf16 v[90:93], v[230:233], v[190:193], v[90:93]
	v_mfma_f32_16x16x32_bf16 v[82:85], v[238:241], v[190:193], v[82:85]
	v_mfma_f32_16x16x32_bf16 v[74:77], v[230:233], v[206:209], v[74:77]
	v_mfma_f32_16x16x32_bf16 v[66:69], v[238:241], v[206:209], v[66:69]
	v_mfma_f32_16x16x32_bf16 v[122:125], v[234:237], v[150:153], v[122:125]
	v_mfma_f32_16x16x32_bf16 v[114:117], v[242:245], v[150:153], v[114:117]
	v_mfma_f32_16x16x32_bf16 v[106:109], v[234:237], v[186:189], v[106:109]
	v_mfma_f32_16x16x32_bf16 v[98:101], v[242:245], v[186:189], v[98:101]
	v_mfma_f32_16x16x32_bf16 v[90:93], v[234:237], v[194:197], v[90:93]
	v_mfma_f32_16x16x32_bf16 v[82:85], v[242:245], v[194:197], v[82:85]
	v_mfma_f32_16x16x32_bf16 v[74:77], v[234:237], v[216:219], v[74:77]
	v_mfma_f32_16x16x32_bf16 v[66:69], v[242:245], v[216:219], v[66:69]
	s_setprio 0
	s_barrier
	ds_read_b128 v[146:149], v205 offset:16384
	ds_read_b128 v[150:153], v205 offset:17408
	ds_read_b128 v[182:185], v205 offset:18432
	ds_read_b128 v[186:189], v205 offset:19456
	ds_read_b128 v[190:193], v205 offset:20480
	ds_read_b128 v[194:197], v205 offset:21504
	ds_read_b128 v[206:209], v205 offset:22528
	ds_read_b128 v[216:219], v205 offset:23552
	s_cbranch_vccz .Lss_i2
	v_lshlrev_b32_e32 v176, 4, v167
	s_lshl_b32 m0, s46, 1
	v_add_u32_e32 v176, s46, v176
	s_add_i32 m0, m0, 0x20000
	s_mov_b64 vcc, 0
	global_load_lds_dwordx4 v176, s[98:99]
	global_load_lds_dwordx4 v176, s[98:99] offset:1024

.LBB0_288:
	s_ashr_i32 s27, s26, 31
	s_lshl_b64 s[22:23], s[26:27], 19
	v_cmp_lt_i64_e32 vcc, s[28:29], v[170:171]
	s_add_u32 s28, s96, s22
	s_addc_u32 s29, s97, s23
	s_and_b64 s[22:23], vcc, exec
	s_cselect_b32 s27, s29, s43
	s_cselect_b32 s50, s28, s42
	s_ashr_i32 s7, s6, 31
	s_lshl_b64 s[22:23], s[6:7], 19
	s_add_u32 s36, s10, s22
	s_addc_u32 s37, s11, s23
	s_and_b64 s[22:23], vcc, exec
	s_cselect_b32 s7, s37, s31
	s_cselect_b32 s51, s36, s30
	s_add_u32 s42, s42, 0x40080
	s_addc_u32 s43, s43, 0
	s_add_u32 s52, s30, 0x100
	s_addc_u32 s53, s31, 0
	s_mov_b32 s54, -2
	s_lshl_b32 s98, s49, 14
	s_add_u32 s98, s100, s98
	s_addc_u32 s99, s101, 0
	s_mov_b64 vcc, -1
	s_cmpk_gt_u32 s0, 0xff
	s_cbranch_scc0 .Lrs_proj0_pre
	s_barrier
.Lrs_proj0_pre:
	s_add_u32 s1, s42, 0xfffc0080
	s_addc_u32 s22, s43, -1
	s_add_i32 s23, 0, 0x10000
	v_add_u32_e32 v142, s23, v217
	ds_read_b128 v[130:133], v142
	ds_read_b128 v[134:137], v142 offset:1024
	ds_read_b128 v[138:141], v142 offset:2048
	ds_read_b128 v[142:145], v142 offset:3072
	s_cmp_eq_u32 s54, 12
	s_cselect_b32 s45, s27, s22
	s_cselect_b32 s44, s50, s1
	s_cselect_b32 s31, s7, s53
	s_cselect_b32 s30, s51, s52
	v_lshl_add_u64 v[176:177], s[42:43], 0, v[190:191]
	s_add_i32 m0, s16, 0xc000
	ds_read_b128 v[146:149], v219
	ds_read_b128 v[150:153], v219 offset:1024
	ds_read_b128 v[154:157], v219 offset:2048
	ds_read_b128 v[158:161], v219 offset:3072
	ds_read_b128 v[194:197], v219 offset:4096
	ds_read_b128 v[198:201], v219 offset:5120
	ds_read_b128 v[202:205], v219 offset:6144
	ds_read_b128 v[206:209], v219 offset:7168
	global_load_lds_dwordx4 v[176:177], off
	v_lshl_add_u64 v[176:177], s[42:43], 0, v[192:193]
	s_add_i32 m0, s16, 0xe000
	s_nop 0
	global_load_lds_dwordx4 v[176:177], off
	s_add_i32 s1, 0, 0x14000
	v_add_u32_e32 v168, s1, v217
	ds_read_b128 v[230:233], v168
	ds_read_b128 v[234:237], v168 offset:1024
	ds_read_b128 v[238:241], v168 offset:2048
	ds_read_b128 v[242:245], v168 offset:3072
	s_waitcnt vmcnt(8)
	s_waitcnt lgkmcnt(0)
	s_barrier
	s_setprio 1
	v_mfma_f32_16x16x32_bf16 v[126:129], v[130:133], v[146:149], 0
	v_mfma_f32_16x16x32_bf16 v[122:125], v[138:141], v[146:149], 0
	v_mfma_f32_16x16x32_bf16 v[118:121], v[130:133], v[154:157], 0
	v_mfma_f32_16x16x32_bf16 v[110:113], v[138:141], v[154:157], 0
	v_mfma_f32_16x16x32_bf16 v[102:105], v[130:133], v[194:197], 0
	v_mfma_f32_16x16x32_bf16 v[94:97], v[138:141], v[194:197], 0
	v_mfma_f32_16x16x32_bf16 v[86:89], v[130:133], v[202:205], 0
	v_mfma_f32_16x16x32_bf16 v[78:81], v[138:141], v[202:205], 0
	v_mfma_f32_16x16x32_bf16 v[126:129], v[134:137], v[150:153], v[126:129]
	v_mfma_f32_16x16x32_bf16 v[122:125], v[142:145], v[150:153], v[122:125]
	v_mfma_f32_16x16x32_bf16 v[118:121], v[134:137], v[158:161], v[118:121]
	v_mfma_f32_16x16x32_bf16 v[110:113], v[142:145], v[158:161], v[110:113]
	v_mfma_f32_16x16x32_bf16 v[102:105], v[134:137], v[198:201], v[102:105]
	v_mfma_f32_16x16x32_bf16 v[94:97], v[142:145], v[198:201], v[94:97]
	v_mfma_f32_16x16x32_bf16 v[86:89], v[134:137], v[206:209], v[86:89]
	v_mfma_f32_16x16x32_bf16 v[78:81], v[142:145], v[206:209], v[78:81]
	v_mfma_f32_16x16x32_bf16 v[114:117], v[230:233], v[146:149], 0
	v_mfma_f32_16x16x32_bf16 v[106:109], v[238:241], v[146:149], 0
	v_mfma_f32_16x16x32_bf16 v[98:101], v[230:233], v[154:157], 0
	v_mfma_f32_16x16x32_bf16 v[90:93], v[238:241], v[154:157], 0
	v_mfma_f32_16x16x32_bf16 v[82:85], v[230:233], v[194:197], 0
	v_mfma_f32_16x16x32_bf16 v[74:77], v[238:241], v[194:197], 0
	v_mfma_f32_16x16x32_bf16 v[70:73], v[230:233], v[202:205], 0
	v_mfma_f32_16x16x32_bf16 v[66:69], v[238:241], v[202:205], 0
	v_mfma_f32_16x16x32_bf16 v[114:117], v[234:237], v[150:153], v[114:117]
	v_mfma_f32_16x16x32_bf16 v[106:109], v[242:245], v[150:153], v[106:109]
	v_mfma_f32_16x16x32_bf16 v[98:101], v[234:237], v[158:161], v[98:101]
	v_mfma_f32_16x16x32_bf16 v[90:93], v[242:245], v[158:161], v[90:93]
	v_mfma_f32_16x16x32_bf16 v[82:85], v[234:237], v[198:201], v[82:85]
	v_mfma_f32_16x16x32_bf16 v[74:77], v[242:245], v[198:201], v[74:77]
	v_mfma_f32_16x16x32_bf16 v[70:73], v[234:237], v[206:209], v[70:73]
	v_mfma_f32_16x16x32_bf16 v[66:69], v[242:245], v[206:209], v[66:69]
	s_setprio 0
	s_barrier
	ds_read_b128 v[146:149], v219 offset:16384
	ds_read_b128 v[150:153], v219 offset:17408
	ds_read_b128 v[154:157], v219 offset:18432
	ds_read_b128 v[158:161], v219 offset:19456
	ds_read_b128 v[194:197], v219 offset:20480
	ds_read_b128 v[198:201], v219 offset:21504
	ds_read_b128 v[202:205], v219 offset:22528
	ds_read_b128 v[206:209], v219 offset:23552
	s_cbranch_vccz .Lss_proj0
	v_lshlrev_b32_e32 v176, 4, v167
	s_lshl_b32 m0, s16, 1
	v_add_u32_e32 v176, s16, v176
	s_add_i32 m0, m0, 0x20000
	s_mov_b64 vcc, 0
	global_load_lds_dwordx4 v176, s[98:99]
	global_load_lds_dwordx4 v176, s[98:99] offset:1024
	s_add_i32 s22, s23, s4
	v_lshl_add_u64 v[176:177], s[30:31], 0, v[0:1]
	s_mov_b32 m0, s22
	s_nop 0
	global_load_lds_dwordx4 v[176:177], off
	v_lshl_add_u64 v[220:221], s[30:31], 0, v[178:179]
	s_add_i32 m0, s22, 0x2000
	s_nop 0
	global_load_lds_dwordx4 v[220:221], off
	s_mov_b32 m0, s16
	v_lshl_add_u64 v[246:247], s[44:45], 0, v[182:183]
	global_load_lds_dwordx4 v[246:247], off
	v_lshl_add_u64 v[248:249], s[44:45], 0, v[180:181]
	s_mov_b32 m0, s17
	s_nop 0
	global_load_lds_dwordx4 v[248:249], off
	s_add_u32 s22, s30, 0x40000
	s_addc_u32 s23, s31, 0
	s_add_i32 s1, s1, s4
	s_mov_b32 m0, s1
	s_nop 0
	global_load_lds_dwordx4 v0, s[22:23]
	s_add_i32 m0, s1, 0x2000
	s_nop 0
	global_load_lds_dwordx4 v178, s[22:23]
	s_waitcnt vmcnt(8)
	s_waitcnt lgkmcnt(0)
	s_barrier
	s_setprio 1
	v_mfma_f32_16x16x32_bf16 v[62:65], v[130:133], v[146:149], 0
	v_mfma_f32_16x16x32_bf16 v[58:61], v[138:141], v[146:149], 0
	v_mfma_f32_16x16x32_bf16 v[54:57], v[130:133], v[154:157], 0
	v_mfma_f32_16x16x32_bf16 v[46:49], v[138:141], v[154:157], 0
	v_mfma_f32_16x16x32_bf16 v[38:41], v[130:133], v[194:197], 0
	v_mfma_f32_16x16x32_bf16 v[30:33], v[138:141], v[194:197], 0
	v_mfma_f32_16x16x32_bf16 v[22:25], v[130:133], v[202:205], 0
	v_mfma_f32_16x16x32_bf16 v[14:17], v[138:141], v[202:205], 0
	v_mfma_f32_16x16x32_bf16 v[62:65], v[134:137], v[150:153], v[62:65]
	v_mfma_f32_16x16x32_bf16 v[58:61], v[142:145], v[150:153], v[58:61]
	v_mfma_f32_16x16x32_bf16 v[54:57], v[134:137], v[158:161], v[54:57]
	v_mfma_f32_16x16x32_bf16 v[46:49], v[142:145], v[158:161], v[46:49]
	v_mfma_f32_16x16x32_bf16 v[38:41], v[134:137], v[198:201], v[38:41]
	v_mfma_f32_16x16x32_bf16 v[30:33], v[142:145], v[198:201], v[30:33]
	v_mfma_f32_16x16x32_bf16 v[22:25], v[134:137], v[206:209], v[22:25]
	v_mfma_f32_16x16x32_bf16 v[14:17], v[142:145], v[206:209], v[14:17]
	v_mfma_f32_16x16x32_bf16 v[50:53], v[230:233], v[146:149], 0
	v_mfma_f32_16x16x32_bf16 v[42:45], v[238:241], v[146:149], 0
	v_mfma_f32_16x16x32_bf16 v[34:37], v[230:233], v[154:157], 0
	v_mfma_f32_16x16x32_bf16 v[26:29], v[238:241], v[154:157], 0
	v_mfma_f32_16x16x32_bf16 v[18:21], v[230:233], v[194:197], 0
	v_mfma_f32_16x16x32_bf16 v[10:13], v[238:241], v[194:197], 0
	v_mfma_f32_16x16x32_bf16 v[6:9], v[230:233], v[202:205], 0
	v_mfma_f32_16x16x32_bf16 v[2:5], v[238:241], v[202:205], 0
	v_mfma_f32_16x16x32_bf16 v[50:53], v[234:237], v[150:153], v[50:53]
	v_mfma_f32_16x16x32_bf16 v[42:45], v[242:245], v[150:153], v[42:45]
	v_mfma_f32_16x16x32_bf16 v[34:37], v[234:237], v[158:161], v[34:37]
	v_mfma_f32_16x16x32_bf16 v[26:29], v[242:245], v[158:161], v[26:29]
	v_mfma_f32_16x16x32_bf16 v[18:21], v[234:237], v[198:201], v[18:21]
	v_mfma_f32_16x16x32_bf16 v[10:13], v[242:245], v[198:201], v[10:13]
	v_mfma_f32_16x16x32_bf16 v[6:9], v[234:237], v[206:209], v[6:9]
	v_mfma_f32_16x16x32_bf16 v[2:5], v[242:245], v[206:209], v[2:5]
	s_setprio 0
	s_barrier
	s_add_i32 s1, 0, 0x18000
	v_add_u32_e32 v142, s1, v217
	ds_read_b128 v[130:133], v142
	ds_read_b128 v[134:137], v142 offset:1024
	ds_read_b128 v[138:141], v142 offset:2048
	ds_read_b128 v[142:145], v142 offset:3072
	s_add_u32 s22, s44, 0x40000
	s_addc_u32 s23, s45, 0
	s_mov_b32 m0, s20
	v_lshl_add_u64 v[230:231], s[22:23], 0, v[182:183]
	ds_read_b128 v[146:149], v219 offset:32768
	ds_read_b128 v[150:153], v219 offset:33792
	ds_read_b128 v[154:157], v219 offset:34816
	ds_read_b128 v[158:161], v219 offset:35840
	ds_read_b128 v[194:197], v219 offset:36864
	ds_read_b128 v[198:201], v219 offset:37888
	ds_read_b128 v[202:205], v219 offset:38912
	ds_read_b128 v[206:209], v219 offset:39936
	global_load_lds_dwordx4 v[230:231], off
	v_lshl_add_u64 v[230:231], s[22:23], 0, v[180:181]
	s_mov_b32 m0, s21
	s_nop 0
	global_load_lds_dwordx4 v[230:231], off
	s_add_i32 s33, 0, 0x1c000
	v_add_u32_e32 v168, s33, v217
	ds_read_b128 v[230:233], v168
	ds_read_b128 v[234:237], v168 offset:1024
	ds_read_b128 v[238:241], v168 offset:2048
	ds_read_b128 v[242:245], v168 offset:3072
	s_waitcnt vmcnt(8)
	s_waitcnt lgkmcnt(0)
	s_barrier
	s_setprio 1
	v_mfma_f32_16x16x32_bf16 v[126:129], v[130:133], v[146:149], v[126:129]
	v_mfma_f32_16x16x32_bf16 v[122:125], v[138:141], v[146:149], v[122:125]
	v_mfma_f32_16x16x32_bf16 v[118:121], v[130:133], v[154:157], v[118:121]
	v_mfma_f32_16x16x32_bf16 v[110:113], v[138:141], v[154:157], v[110:113]
	v_mfma_f32_16x16x32_bf16 v[102:105], v[130:133], v[194:197], v[102:105]
	v_mfma_f32_16x16x32_bf16 v[94:97], v[138:141], v[194:197], v[94:97]
	v_mfma_f32_16x16x32_bf16 v[86:89], v[130:133], v[202:205], v[86:89]
	v_mfma_f32_16x16x32_bf16 v[78:81], v[138:141], v[202:205], v[78:81]
	v_mfma_f32_16x16x32_bf16 v[126:129], v[134:137], v[150:153], v[126:129]
	v_mfma_f32_16x16x32_bf16 v[122:125], v[142:145], v[150:153], v[122:125]
	v_mfma_f32_16x16x32_bf16 v[118:121], v[134:137], v[158:161], v[118:121]
	v_mfma_f32_16x16x32_bf16 v[110:113], v[142:145], v[158:161], v[110:113]
	v_mfma_f32_16x16x32_bf16 v[102:105], v[134:137], v[198:201], v[102:105]
	v_mfma_f32_16x16x32_bf16 v[94:97], v[142:145], v[198:201], v[94:97]
	v_mfma_f32_16x16x32_bf16 v[86:89], v[134:137], v[206:209], v[86:89]
	v_mfma_f32_16x16x32_bf16 v[78:81], v[142:145], v[206:209], v[78:81]
	v_mfma_f32_16x16x32_bf16 v[114:117], v[230:233], v[146:149], v[114:117]
	v_mfma_f32_16x16x32_bf16 v[106:109], v[238:241], v[146:149], v[106:109]
	v_mfma_f32_16x16x32_bf16 v[98:101], v[230:233], v[154:157], v[98:101]
	v_mfma_f32_16x16x32_bf16 v[90:93], v[238:241], v[154:157], v[90:93]
	v_mfma_f32_16x16x32_bf16 v[82:85], v[230:233], v[194:197], v[82:85]
	v_mfma_f32_16x16x32_bf16 v[74:77], v[238:241], v[194:197], v[74:77]
	v_mfma_f32_16x16x32_bf16 v[70:73], v[230:233], v[202:205], v[70:73]
	v_mfma_f32_16x16x32_bf16 v[66:69], v[238:241], v[202:205], v[66:69]
	v_mfma_f32_16x16x32_bf16 v[114:117], v[234:237], v[150:153], v[114:117]
	v_mfma_f32_16x16x32_bf16 v[106:109], v[242:245], v[150:153], v[106:109]
	v_mfma_f32_16x16x32_bf16 v[98:101], v[234:237], v[158:161], v[98:101]
	v_mfma_f32_16x16x32_bf16 v[90:93], v[242:245], v[158:161], v[90:93]
	v_mfma_f32_16x16x32_bf16 v[82:85], v[234:237], v[198:201], v[82:85]
	v_mfma_f32_16x16x32_bf16 v[74:77], v[242:245], v[198:201], v[74:77]
	v_mfma_f32_16x16x32_bf16 v[70:73], v[234:237], v[206:209], v[70:73]
	v_mfma_f32_16x16x32_bf16 v[66:69], v[242:245], v[206:209], v[66:69]
	s_setprio 0
	s_barrier
	ds_read_b128 v[146:149], v219 offset:49152
	ds_read_b128 v[150:153], v219 offset:50176
	ds_read_b128 v[154:157], v219 offset:51200
	ds_read_b128 v[158:161], v219 offset:52224
	ds_read_b128 v[194:197], v219 offset:53248
	ds_read_b128 v[198:201], v219 offset:54272
	ds_read_b128 v[202:205], v219 offset:55296
	ds_read_b128 v[206:209], v219 offset:56320
	s_add_i32 s1, s1, s4
	v_lshl_add_u64 v[176:177], v[176:177], 0, s[12:13]
	s_mov_b32 m0, s1
	s_nop 0
	global_load_lds_dwordx4 v[176:177], off
	v_lshl_add_u64 v[176:177], v[220:221], 0, s[12:13]
	s_add_i32 m0, s1, 0x2000
	s_nop 0
	global_load_lds_dwordx4 v[176:177], off
	s_mov_b32 m0, s34
	v_lshl_add_u64 v[176:177], v[246:247], 0, s[12:13]
	global_load_lds_dwordx4 v[176:177], off
	v_lshl_add_u64 v[176:177], v[248:249], 0, s[12:13]
	s_mov_b32 m0, s46
	s_nop 0
	global_load_lds_dwordx4 v[176:177], off
	s_add_u32 s22, s30, 0x40080
	s_addc_u32 s23, s31, 0
	s_add_i32 s1, s33, s4
	s_mov_b32 m0, s1
	s_nop 0
	global_load_lds_dwordx4 v0, s[22:23]
	s_add_i32 m0, s1, 0x2000
	s_nop 0
	global_load_lds_dwordx4 v178, s[22:23]
	s_waitcnt vmcnt(8)
	s_waitcnt lgkmcnt(0)
	s_barrier
	s_setprio 1
	v_mfma_f32_16x16x32_bf16 v[62:65], v[130:133], v[146:149], v[62:65]
	v_mfma_f32_16x16x32_bf16 v[58:61], v[138:141], v[146:149], v[58:61]
	v_mfma_f32_16x16x32_bf16 v[54:57], v[130:133], v[154:157], v[54:57]
	v_mfma_f32_16x16x32_bf16 v[46:49], v[138:141], v[154:157], v[46:49]
	v_mfma_f32_16x16x32_bf16 v[38:41], v[130:133], v[194:197], v[38:41]
	v_mfma_f32_16x16x32_bf16 v[30:33], v[138:141], v[194:197], v[30:33]
	v_mfma_f32_16x16x32_bf16 v[22:25], v[130:133], v[202:205], v[22:25]
	v_mfma_f32_16x16x32_bf16 v[14:17], v[138:141], v[202:205], v[14:17]
	v_mfma_f32_16x16x32_bf16 v[62:65], v[134:137], v[150:153], v[62:65]
	v_mfma_f32_16x16x32_bf16 v[58:61], v[142:145], v[150:153], v[58:61]
	v_mfma_f32_16x16x32_bf16 v[54:57], v[134:137], v[158:161], v[54:57]
	v_mfma_f32_16x16x32_bf16 v[46:49], v[142:145], v[158:161], v[46:49]
	v_mfma_f32_16x16x32_bf16 v[38:41], v[134:137], v[198:201], v[38:41]
	v_mfma_f32_16x16x32_bf16 v[30:33], v[142:145], v[198:201], v[30:33]
	v_mfma_f32_16x16x32_bf16 v[22:25], v[134:137], v[206:209], v[22:25]
	v_mfma_f32_16x16x32_bf16 v[14:17], v[142:145], v[206:209], v[14:17]
	v_mfma_f32_16x16x32_bf16 v[50:53], v[230:233], v[146:149], v[50:53]
	v_mfma_f32_16x16x32_bf16 v[42:45], v[238:241], v[146:149], v[42:45]
	v_mfma_f32_16x16x32_bf16 v[34:37], v[230:233], v[154:157], v[34:37]
	v_mfma_f32_16x16x32_bf16 v[26:29], v[238:241], v[154:157], v[26:29]
	v_mfma_f32_16x16x32_bf16 v[18:21], v[230:233], v[194:197], v[18:21]
	v_mfma_f32_16x16x32_bf16 v[10:13], v[238:241], v[194:197], v[10:13]
	v_mfma_f32_16x16x32_bf16 v[6:9], v[230:233], v[202:205], v[6:9]
	v_mfma_f32_16x16x32_bf16 v[2:5], v[238:241], v[202:205], v[2:5]
	v_mfma_f32_16x16x32_bf16 v[50:53], v[234:237], v[150:153], v[50:53]
	v_mfma_f32_16x16x32_bf16 v[42:45], v[242:245], v[150:153], v[42:45]
	v_mfma_f32_16x16x32_bf16 v[34:37], v[234:237], v[158:161], v[34:37]
	v_mfma_f32_16x16x32_bf16 v[26:29], v[242:245], v[158:161], v[26:29]
	v_mfma_f32_16x16x32_bf16 v[18:21], v[234:237], v[198:201], v[18:21]
	v_mfma_f32_16x16x32_bf16 v[10:13], v[242:245], v[198:201], v[10:13]
	v_mfma_f32_16x16x32_bf16 v[6:9], v[234:237], v[206:209], v[6:9]
	v_mfma_f32_16x16x32_bf16 v[2:5], v[242:245], v[206:209], v[2:5]
	s_setprio 0
	s_add_i32 s54, s54, 2
	s_add_u32 s42, s42, 0x100
	s_addc_u32 s43, s43, 0
	s_add_u32 s52, s52, 0x100
	s_addc_u32 s53, s53, 0
	s_cmp_gt_u32 s54, 13
	s_barrier
.LBB0_289:
	s_add_u32 s1, s42, 0xfffc0080
	s_addc_u32 s22, s43, -1
	s_add_i32 s23, 0, 0x10000
	v_add_u32_e32 v142, s23, v217
	ds_read_b128 v[130:133], v142
	ds_read_b128 v[134:137], v142 offset:1024
	ds_read_b128 v[138:141], v142 offset:2048
	ds_read_b128 v[142:145], v142 offset:3072
	s_cmp_eq_u32 s54, 12
	s_cselect_b32 s45, s27, s22
	s_cselect_b32 s44, s50, s1
	s_cselect_b32 s31, s7, s53
	s_cselect_b32 s30, s51, s52
	v_lshl_add_u64 v[176:177], s[42:43], 0, v[190:191]
	s_add_i32 m0, s16, 0xc000
	ds_read_b128 v[146:149], v219
	ds_read_b128 v[150:153], v219 offset:1024
	ds_read_b128 v[154:157], v219 offset:2048
	ds_read_b128 v[158:161], v219 offset:3072
	ds_read_b128 v[194:197], v219 offset:4096
	ds_read_b128 v[198:201], v219 offset:5120
	ds_read_b128 v[202:205], v219 offset:6144
	ds_read_b128 v[206:209], v219 offset:7168
	global_load_lds_dwordx4 v[176:177], off
	v_lshl_add_u64 v[176:177], s[42:43], 0, v[192:193]
	s_add_i32 m0, s16, 0xe000
	s_nop 0
	global_load_lds_dwordx4 v[176:177], off
	s_add_i32 s1, 0, 0x14000
	v_add_u32_e32 v168, s1, v217
	ds_read_b128 v[230:233], v168
	ds_read_b128 v[234:237], v168 offset:1024
	ds_read_b128 v[238:241], v168 offset:2048
	ds_read_b128 v[242:245], v168 offset:3072
	s_waitcnt vmcnt(8)
	s_waitcnt lgkmcnt(0)
	s_barrier
	s_setprio 1
	v_mfma_f32_16x16x32_bf16 v[126:129], v[130:133], v[146:149], v[126:129]
	v_mfma_f32_16x16x32_bf16 v[122:125], v[138:141], v[146:149], v[122:125]
	v_mfma_f32_16x16x32_bf16 v[118:121], v[130:133], v[154:157], v[118:121]
	v_mfma_f32_16x16x32_bf16 v[110:113], v[138:141], v[154:157], v[110:113]
	v_mfma_f32_16x16x32_bf16 v[102:105], v[130:133], v[194:197], v[102:105]
	v_mfma_f32_16x16x32_bf16 v[94:97], v[138:141], v[194:197], v[94:97]
	v_mfma_f32_16x16x32_bf16 v[86:89], v[130:133], v[202:205], v[86:89]
	v_mfma_f32_16x16x32_bf16 v[78:81], v[138:141], v[202:205], v[78:81]
	v_mfma_f32_16x16x32_bf16 v[126:129], v[134:137], v[150:153], v[126:129]
	v_mfma_f32_16x16x32_bf16 v[122:125], v[142:145], v[150:153], v[122:125]
	v_mfma_f32_16x16x32_bf16 v[118:121], v[134:137], v[158:161], v[118:121]
	v_mfma_f32_16x16x32_bf16 v[110:113], v[142:145], v[158:161], v[110:113]
	v_mfma_f32_16x16x32_bf16 v[102:105], v[134:137], v[198:201], v[102:105]
	v_mfma_f32_16x16x32_bf16 v[94:97], v[142:145], v[198:201], v[94:97]
	v_mfma_f32_16x16x32_bf16 v[86:89], v[134:137], v[206:209], v[86:89]
	v_mfma_f32_16x16x32_bf16 v[78:81], v[142:145], v[206:209], v[78:81]
	v_mfma_f32_16x16x32_bf16 v[114:117], v[230:233], v[146:149], v[114:117]
	v_mfma_f32_16x16x32_bf16 v[106:109], v[238:241], v[146:149], v[106:109]
	v_mfma_f32_16x16x32_bf16 v[98:101], v[230:233], v[154:157], v[98:101]
	v_mfma_f32_16x16x32_bf16 v[90:93], v[238:241], v[154:157], v[90:93]
	v_mfma_f32_16x16x32_bf16 v[82:85], v[230:233], v[194:197], v[82:85]
	v_mfma_f32_16x16x32_bf16 v[74:77], v[238:241], v[194:197], v[74:77]
	v_mfma_f32_16x16x32_bf16 v[70:73], v[230:233], v[202:205], v[70:73]
	v_mfma_f32_16x16x32_bf16 v[66:69], v[238:241], v[202:205], v[66:69]
	v_mfma_f32_16x16x32_bf16 v[114:117], v[234:237], v[150:153], v[114:117]
	v_mfma_f32_16x16x32_bf16 v[106:109], v[242:245], v[150:153], v[106:109]
	v_mfma_f32_16x16x32_bf16 v[98:101], v[234:237], v[158:161], v[98:101]
	v_mfma_f32_16x16x32_bf16 v[90:93], v[242:245], v[158:161], v[90:93]
	v_mfma_f32_16x16x32_bf16 v[82:85], v[234:237], v[198:201], v[82:85]
	v_mfma_f32_16x16x32_bf16 v[74:77], v[242:245], v[198:201], v[74:77]
	v_mfma_f32_16x16x32_bf16 v[70:73], v[234:237], v[206:209], v[70:73]
	v_mfma_f32_16x16x32_bf16 v[66:69], v[242:245], v[206:209], v[66:69]
	s_setprio 0
	s_barrier
	ds_read_b128 v[146:149], v219 offset:16384
	ds_read_b128 v[150:153], v219 offset:17408
	ds_read_b128 v[154:157], v219 offset:18432
	ds_read_b128 v[158:161], v219 offset:19456
	ds_read_b128 v[194:197], v219 offset:20480
	ds_read_b128 v[198:201], v219 offset:21504
	ds_read_b128 v[202:205], v219 offset:22528
	ds_read_b128 v[206:209], v219 offset:23552
	s_cbranch_vccz .Lss_proj0
	v_lshlrev_b32_e32 v176, 4, v167
	s_lshl_b32 m0, s16, 1
	v_add_u32_e32 v176, s16, v176
	s_add_i32 m0, m0, 0x20000
	s_mov_b64 vcc, 0
	global_load_lds_dwordx4 v176, s[98:99]
	global_load_lds_dwordx4 v176, s[98:99] offset:1024

.LBB0_361:
	s_ashr_i32 s25, s24, 31
	s_lshl_b64 s[20:21], s[24:25], 19
	v_cmp_lt_i64_e32 vcc, s[26:27], v[174:175]
	s_add_u32 s26, s46, s20
	s_addc_u32 s27, s47, s21
	s_and_b64 s[20:21], vcc, exec
	s_cselect_b32 s17, s27, s29
	s_cselect_b32 s20, s26, s28
	s_ashr_i32 s9, s8, 31
	s_lshl_b64 s[22:23], s[8:9], 19
	v_readlane_b32 s36, v254, 42
	v_readlane_b32 s37, v254, 43
	s_add_u32 s36, s36, s22
	s_addc_u32 s37, s37, s23
	s_and_b64 s[22:23], vcc, exec
	s_cselect_b32 s9, s37, s31
	s_cselect_b32 s21, s36, s30
	s_add_u32 s28, s28, 0x40080
	s_addc_u32 s29, s29, 0
	s_add_u32 s25, s30, 0x100
	s_addc_u32 s34, s31, 0
	s_mov_b32 s44, -2
	s_lshl_b32 s98, s16, 8
	s_add_i32 s98, s98, s54
	s_lshl_b32 s98, s98, 6
	s_add_u32 s98, s100, s98
	s_addc_u32 s99, s101, 0
	s_mov_b64 vcc, -1
	s_cmpk_gt_u32 s4, 0xff
	s_cbranch_scc0 .Lrs_proj1_pre
	s_barrier
.Lrs_proj1_pre:
	s_add_u32 s1, s28, 0xfffc0080
	s_addc_u32 s22, s29, -1
	s_add_i32 s23, 0, 0x10000
	v_add_u32_e32 v158, s23, v181
	ds_read_b128 v[130:133], v158
	ds_read_b128 v[134:137], v158 offset:1024
	ds_read_b128 v[154:157], v158 offset:2048
	ds_read_b128 v[186:189], v158 offset:3072
	s_cmp_eq_u32 s44, 12
	s_cselect_b32 s43, s17, s22
	s_cselect_b32 s42, s20, s1
	s_cselect_b32 s31, s9, s34
	s_cselect_b32 s30, s21, s25
	v_lshl_add_u64 v[160:161], s[28:29], 0, v[150:151]
	s_add_i32 m0, s49, 0xc000
	ds_read_b128 v[190:193], v185
	ds_read_b128 v[194:197], v185 offset:1024
	ds_read_b128 v[198:201], v185 offset:2048
	ds_read_b128 v[202:205], v185 offset:3072
	ds_read_b128 v[206:209], v185 offset:4096
	ds_read_b128 v[216:219], v185 offset:5120
	ds_read_b128 v[230:233], v185 offset:6144
	ds_read_b128 v[234:237], v185 offset:7168
	global_load_lds_dwordx4 v[160:161], off
	v_lshl_add_u64 v[160:161], s[28:29], 0, v[152:153]
	s_add_i32 m0, s49, 0xe000
	s_nop 0
	global_load_lds_dwordx4 v[160:161], off
	s_add_i32 s1, 0, 0x14000
	v_add_u32_e32 v158, s1, v181
	ds_read_b128 v[238:241], v158
	ds_read_b128 v[242:245], v158 offset:1024
	ds_read_b128 v[246:249], v158 offset:2048
	ds_read_b128 v[176:179], v158 offset:3072
	s_waitcnt vmcnt(8)
	s_waitcnt lgkmcnt(0)
	s_barrier
	s_setprio 1
	v_mfma_f32_16x16x32_bf16 v[126:129], v[130:133], v[190:193], 0
	v_mfma_f32_16x16x32_bf16 v[122:125], v[154:157], v[190:193], 0
	v_mfma_f32_16x16x32_bf16 v[110:113], v[130:133], v[198:201], 0
	v_mfma_f32_16x16x32_bf16 v[106:109], v[154:157], v[198:201], 0
	v_mfma_f32_16x16x32_bf16 v[94:97], v[130:133], v[206:209], 0
	v_mfma_f32_16x16x32_bf16 v[90:93], v[154:157], v[206:209], 0
	v_mfma_f32_16x16x32_bf16 v[78:81], v[130:133], v[230:233], 0
	v_mfma_f32_16x16x32_bf16 v[74:77], v[154:157], v[230:233], 0
	v_mfma_f32_16x16x32_bf16 v[126:129], v[134:137], v[194:197], v[126:129]
	v_mfma_f32_16x16x32_bf16 v[122:125], v[186:189], v[194:197], v[122:125]
	v_mfma_f32_16x16x32_bf16 v[110:113], v[134:137], v[202:205], v[110:113]
	v_mfma_f32_16x16x32_bf16 v[106:109], v[186:189], v[202:205], v[106:109]
	v_mfma_f32_16x16x32_bf16 v[94:97], v[134:137], v[216:219], v[94:97]
	v_mfma_f32_16x16x32_bf16 v[90:93], v[186:189], v[216:219], v[90:93]
	v_mfma_f32_16x16x32_bf16 v[78:81], v[134:137], v[234:237], v[78:81]
	v_mfma_f32_16x16x32_bf16 v[74:77], v[186:189], v[234:237], v[74:77]
	v_mfma_f32_16x16x32_bf16 v[118:121], v[238:241], v[190:193], 0
	v_mfma_f32_16x16x32_bf16 v[114:117], v[246:249], v[190:193], 0
	v_mfma_f32_16x16x32_bf16 v[102:105], v[238:241], v[198:201], 0
	v_mfma_f32_16x16x32_bf16 v[98:101], v[246:249], v[198:201], 0
	v_mfma_f32_16x16x32_bf16 v[86:89], v[238:241], v[206:209], 0
	v_mfma_f32_16x16x32_bf16 v[82:85], v[246:249], v[206:209], 0
	v_mfma_f32_16x16x32_bf16 v[70:73], v[238:241], v[230:233], 0
	v_mfma_f32_16x16x32_bf16 v[66:69], v[246:249], v[230:233], 0
	v_mfma_f32_16x16x32_bf16 v[118:121], v[242:245], v[194:197], v[118:121]
	v_mfma_f32_16x16x32_bf16 v[114:117], v[176:179], v[194:197], v[114:117]
	v_mfma_f32_16x16x32_bf16 v[102:105], v[242:245], v[202:205], v[102:105]
	v_mfma_f32_16x16x32_bf16 v[98:101], v[176:179], v[202:205], v[98:101]
	v_mfma_f32_16x16x32_bf16 v[86:89], v[242:245], v[216:219], v[86:89]
	v_mfma_f32_16x16x32_bf16 v[82:85], v[176:179], v[216:219], v[82:85]
	v_mfma_f32_16x16x32_bf16 v[70:73], v[242:245], v[234:237], v[70:73]
	v_mfma_f32_16x16x32_bf16 v[66:69], v[176:179], v[234:237], v[66:69]
	s_setprio 0
	s_barrier
	ds_read_b128 v[190:193], v185 offset:16384
	ds_read_b128 v[194:197], v185 offset:17408
	ds_read_b128 v[198:201], v185 offset:18432
	ds_read_b128 v[202:205], v185 offset:19456
	ds_read_b128 v[206:209], v185 offset:20480
	ds_read_b128 v[216:219], v185 offset:21504
	ds_read_b128 v[230:233], v185 offset:22528
	ds_read_b128 v[234:237], v185 offset:23552
	s_cbranch_vccz .Lss_proj1
	v_lshlrev_b32_e32 v160, 4, v167
	s_lshl_b32 m0, s49, 1
	v_add_u32_e32 v160, s49, v160
	s_add_i32 m0, m0, 0x20000
	s_mov_b64 vcc, 0
	global_load_lds_dwordx4 v160, s[98:99]
	global_load_lds_dwordx4 v160, s[98:99] offset:1024
	s_add_i32 s22, s23, s48
	v_lshl_add_u64 v[160:161], s[30:31], 0, v[0:1]
	s_mov_b32 m0, s22
	s_nop 0
	global_load_lds_dwordx4 v[160:161], off
	v_lshl_add_u64 v[220:221], s[30:31], 0, v[138:139]
	s_add_i32 m0, s22, 0x2000
	s_nop 0
	global_load_lds_dwordx4 v[220:221], off
	s_mov_b32 m0, s49
	v_lshl_add_u64 v[250:251], s[42:43], 0, v[142:143]
	global_load_lds_dwordx4 v[250:251], off
	v_lshl_add_u64 v[168:169], s[42:43], 0, v[140:141]
	s_mov_b32 m0, s50
	s_nop 0
	global_load_lds_dwordx4 v[168:169], off
	s_add_u32 s22, s30, 0x40000
	s_addc_u32 s23, s31, 0
	s_add_i32 s1, s1, s48
	s_mov_b32 m0, s1
	s_nop 0
	global_load_lds_dwordx4 v0, s[22:23]
	s_add_i32 m0, s1, 0x2000
	s_nop 0
	global_load_lds_dwordx4 v138, s[22:23]
	s_waitcnt vmcnt(8)
	s_waitcnt lgkmcnt(0)
	s_barrier
	s_setprio 1
	v_mfma_f32_16x16x32_bf16 v[62:65], v[130:133], v[190:193], 0
	v_mfma_f32_16x16x32_bf16 v[58:61], v[154:157], v[190:193], 0
	v_mfma_f32_16x16x32_bf16 v[46:49], v[130:133], v[198:201], 0
	v_mfma_f32_16x16x32_bf16 v[42:45], v[154:157], v[198:201], 0
	v_mfma_f32_16x16x32_bf16 v[30:33], v[130:133], v[206:209], 0
	v_mfma_f32_16x16x32_bf16 v[26:29], v[154:157], v[206:209], 0
	v_mfma_f32_16x16x32_bf16 v[14:17], v[130:133], v[230:233], 0
	v_mfma_f32_16x16x32_bf16 v[10:13], v[154:157], v[230:233], 0
	v_mfma_f32_16x16x32_bf16 v[62:65], v[134:137], v[194:197], v[62:65]
	v_mfma_f32_16x16x32_bf16 v[58:61], v[186:189], v[194:197], v[58:61]
	v_mfma_f32_16x16x32_bf16 v[46:49], v[134:137], v[202:205], v[46:49]
	v_mfma_f32_16x16x32_bf16 v[42:45], v[186:189], v[202:205], v[42:45]
	v_mfma_f32_16x16x32_bf16 v[30:33], v[134:137], v[216:219], v[30:33]
	v_mfma_f32_16x16x32_bf16 v[26:29], v[186:189], v[216:219], v[26:29]
	v_mfma_f32_16x16x32_bf16 v[14:17], v[134:137], v[234:237], v[14:17]
	v_mfma_f32_16x16x32_bf16 v[10:13], v[186:189], v[234:237], v[10:13]
	v_mfma_f32_16x16x32_bf16 v[54:57], v[238:241], v[190:193], 0
	v_mfma_f32_16x16x32_bf16 v[50:53], v[246:249], v[190:193], 0
	v_mfma_f32_16x16x32_bf16 v[38:41], v[238:241], v[198:201], 0
	v_mfma_f32_16x16x32_bf16 v[34:37], v[246:249], v[198:201], 0
	v_mfma_f32_16x16x32_bf16 v[22:25], v[238:241], v[206:209], 0
	v_mfma_f32_16x16x32_bf16 v[18:21], v[246:249], v[206:209], 0
	v_mfma_f32_16x16x32_bf16 v[6:9], v[238:241], v[230:233], 0
	v_mfma_f32_16x16x32_bf16 v[2:5], v[246:249], v[230:233], 0
	v_mfma_f32_16x16x32_bf16 v[54:57], v[242:245], v[194:197], v[54:57]
	v_mfma_f32_16x16x32_bf16 v[50:53], v[176:179], v[194:197], v[50:53]
	v_mfma_f32_16x16x32_bf16 v[38:41], v[242:245], v[202:205], v[38:41]
	v_mfma_f32_16x16x32_bf16 v[34:37], v[176:179], v[202:205], v[34:37]
	v_mfma_f32_16x16x32_bf16 v[22:25], v[242:245], v[216:219], v[22:25]
	v_mfma_f32_16x16x32_bf16 v[18:21], v[176:179], v[216:219], v[18:21]
	v_mfma_f32_16x16x32_bf16 v[6:9], v[242:245], v[234:237], v[6:9]
	v_mfma_f32_16x16x32_bf16 v[2:5], v[176:179], v[234:237], v[2:5]
	s_setprio 0
	s_barrier
	s_add_i32 s1, 0, 0x18000
	v_add_u32_e32 v158, s1, v181
	ds_read_b128 v[130:133], v158
	ds_read_b128 v[134:137], v158 offset:1024
	ds_read_b128 v[154:157], v158 offset:2048
	ds_read_b128 v[176:179], v158 offset:3072
	s_add_u32 s22, s42, 0x40000
	s_addc_u32 s23, s43, 0
	s_mov_b32 m0, s51
	v_lshl_add_u64 v[234:235], s[22:23], 0, v[142:143]
	ds_read_b128 v[186:189], v185 offset:32768
	ds_read_b128 v[190:193], v185 offset:33792
	ds_read_b128 v[194:197], v185 offset:34816
	ds_read_b128 v[198:201], v185 offset:35840
	ds_read_b128 v[202:205], v185 offset:36864
	ds_read_b128 v[206:209], v185 offset:37888
	ds_read_b128 v[216:219], v185 offset:38912
	ds_read_b128 v[230:233], v185 offset:39936
	global_load_lds_dwordx4 v[234:235], off
	v_lshl_add_u64 v[234:235], s[22:23], 0, v[140:141]
	s_mov_b32 m0, s52
	s_nop 0
	global_load_lds_dwordx4 v[234:235], off
	s_add_i32 s33, 0, 0x1c000
	v_add_u32_e32 v158, s33, v181
	ds_read_b128 v[234:237], v158
	ds_read_b128 v[238:241], v158 offset:1024
	ds_read_b128 v[242:245], v158 offset:2048
	ds_read_b128 v[246:249], v158 offset:3072
	s_waitcnt vmcnt(8)
	s_waitcnt lgkmcnt(0)
	s_barrier
	s_setprio 1
	v_mfma_f32_16x16x32_bf16 v[126:129], v[130:133], v[186:189], v[126:129]
	v_mfma_f32_16x16x32_bf16 v[122:125], v[154:157], v[186:189], v[122:125]
	v_mfma_f32_16x16x32_bf16 v[110:113], v[130:133], v[194:197], v[110:113]
	v_mfma_f32_16x16x32_bf16 v[106:109], v[154:157], v[194:197], v[106:109]
	v_mfma_f32_16x16x32_bf16 v[94:97], v[130:133], v[202:205], v[94:97]
	v_mfma_f32_16x16x32_bf16 v[90:93], v[154:157], v[202:205], v[90:93]
	v_mfma_f32_16x16x32_bf16 v[78:81], v[130:133], v[216:219], v[78:81]
	v_mfma_f32_16x16x32_bf16 v[74:77], v[154:157], v[216:219], v[74:77]
	v_mfma_f32_16x16x32_bf16 v[126:129], v[134:137], v[190:193], v[126:129]
	v_mfma_f32_16x16x32_bf16 v[122:125], v[176:179], v[190:193], v[122:125]
	v_mfma_f32_16x16x32_bf16 v[110:113], v[134:137], v[198:201], v[110:113]
	v_mfma_f32_16x16x32_bf16 v[106:109], v[176:179], v[198:201], v[106:109]
	v_mfma_f32_16x16x32_bf16 v[94:97], v[134:137], v[206:209], v[94:97]
	v_mfma_f32_16x16x32_bf16 v[90:93], v[176:179], v[206:209], v[90:93]
	v_mfma_f32_16x16x32_bf16 v[78:81], v[134:137], v[230:233], v[78:81]
	v_mfma_f32_16x16x32_bf16 v[74:77], v[176:179], v[230:233], v[74:77]
	v_mfma_f32_16x16x32_bf16 v[118:121], v[234:237], v[186:189], v[118:121]
	v_mfma_f32_16x16x32_bf16 v[114:117], v[242:245], v[186:189], v[114:117]
	v_mfma_f32_16x16x32_bf16 v[102:105], v[234:237], v[194:197], v[102:105]
	v_mfma_f32_16x16x32_bf16 v[98:101], v[242:245], v[194:197], v[98:101]
	v_mfma_f32_16x16x32_bf16 v[86:89], v[234:237], v[202:205], v[86:89]
	v_mfma_f32_16x16x32_bf16 v[82:85], v[242:245], v[202:205], v[82:85]
	v_mfma_f32_16x16x32_bf16 v[70:73], v[234:237], v[216:219], v[70:73]
	v_mfma_f32_16x16x32_bf16 v[66:69], v[242:245], v[216:219], v[66:69]
	v_mfma_f32_16x16x32_bf16 v[118:121], v[238:241], v[190:193], v[118:121]
	v_mfma_f32_16x16x32_bf16 v[114:117], v[246:249], v[190:193], v[114:117]
	v_mfma_f32_16x16x32_bf16 v[102:105], v[238:241], v[198:201], v[102:105]
	v_mfma_f32_16x16x32_bf16 v[98:101], v[246:249], v[198:201], v[98:101]
	v_mfma_f32_16x16x32_bf16 v[86:89], v[238:241], v[206:209], v[86:89]
	v_mfma_f32_16x16x32_bf16 v[82:85], v[246:249], v[206:209], v[82:85]
	v_mfma_f32_16x16x32_bf16 v[70:73], v[238:241], v[230:233], v[70:73]
	v_mfma_f32_16x16x32_bf16 v[66:69], v[246:249], v[230:233], v[66:69]
	s_setprio 0
	s_barrier
	ds_read_b128 v[186:189], v185 offset:49152
	ds_read_b128 v[190:193], v185 offset:50176
	ds_read_b128 v[194:197], v185 offset:51200
	ds_read_b128 v[198:201], v185 offset:52224
	ds_read_b128 v[202:205], v185 offset:53248
	ds_read_b128 v[206:209], v185 offset:54272
	ds_read_b128 v[216:219], v185 offset:55296
	ds_read_b128 v[230:233], v185 offset:56320
	s_add_i32 s1, s1, s48
	v_lshl_add_u64 v[160:161], v[160:161], 0, s[12:13]
	s_mov_b32 m0, s1
	s_nop 0
	global_load_lds_dwordx4 v[160:161], off
	v_lshl_add_u64 v[160:161], v[220:221], 0, s[12:13]
	s_add_i32 m0, s1, 0x2000
	s_nop 0
	global_load_lds_dwordx4 v[160:161], off
	s_mov_b32 m0, s55
	v_lshl_add_u64 v[160:161], v[250:251], 0, s[12:13]
	global_load_lds_dwordx4 v[160:161], off
	v_lshl_add_u64 v[160:161], v[168:169], 0, s[12:13]
	s_mov_b32 m0, s56
	s_nop 0
	global_load_lds_dwordx4 v[160:161], off
	s_add_u32 s22, s30, 0x40080
	s_addc_u32 s23, s31, 0
	s_add_i32 s1, s33, s48
	s_mov_b32 m0, s1
	s_nop 0
	global_load_lds_dwordx4 v0, s[22:23]
	s_add_i32 m0, s1, 0x2000
	s_nop 0
	global_load_lds_dwordx4 v138, s[22:23]
	s_waitcnt vmcnt(8)
	s_waitcnt lgkmcnt(0)
	s_barrier
	s_setprio 1
	v_mfma_f32_16x16x32_bf16 v[62:65], v[130:133], v[186:189], v[62:65]
	v_mfma_f32_16x16x32_bf16 v[58:61], v[154:157], v[186:189], v[58:61]
	v_mfma_f32_16x16x32_bf16 v[46:49], v[130:133], v[194:197], v[46:49]
	v_mfma_f32_16x16x32_bf16 v[42:45], v[154:157], v[194:197], v[42:45]
	v_mfma_f32_16x16x32_bf16 v[30:33], v[130:133], v[202:205], v[30:33]
	v_mfma_f32_16x16x32_bf16 v[26:29], v[154:157], v[202:205], v[26:29]
	v_mfma_f32_16x16x32_bf16 v[14:17], v[130:133], v[216:219], v[14:17]
	v_mfma_f32_16x16x32_bf16 v[10:13], v[154:157], v[216:219], v[10:13]
	v_mfma_f32_16x16x32_bf16 v[62:65], v[134:137], v[190:193], v[62:65]
	v_mfma_f32_16x16x32_bf16 v[58:61], v[176:179], v[190:193], v[58:61]
	v_mfma_f32_16x16x32_bf16 v[46:49], v[134:137], v[198:201], v[46:49]
	v_mfma_f32_16x16x32_bf16 v[42:45], v[176:179], v[198:201], v[42:45]
	v_mfma_f32_16x16x32_bf16 v[30:33], v[134:137], v[206:209], v[30:33]
	v_mfma_f32_16x16x32_bf16 v[26:29], v[176:179], v[206:209], v[26:29]
	v_mfma_f32_16x16x32_bf16 v[14:17], v[134:137], v[230:233], v[14:17]
	v_mfma_f32_16x16x32_bf16 v[10:13], v[176:179], v[230:233], v[10:13]
	v_mfma_f32_16x16x32_bf16 v[54:57], v[234:237], v[186:189], v[54:57]
	v_mfma_f32_16x16x32_bf16 v[50:53], v[242:245], v[186:189], v[50:53]
	v_mfma_f32_16x16x32_bf16 v[38:41], v[234:237], v[194:197], v[38:41]
	v_mfma_f32_16x16x32_bf16 v[34:37], v[242:245], v[194:197], v[34:37]
	v_mfma_f32_16x16x32_bf16 v[22:25], v[234:237], v[202:205], v[22:25]
	v_mfma_f32_16x16x32_bf16 v[18:21], v[242:245], v[202:205], v[18:21]
	v_mfma_f32_16x16x32_bf16 v[6:9], v[234:237], v[216:219], v[6:9]
	v_mfma_f32_16x16x32_bf16 v[2:5], v[242:245], v[216:219], v[2:5]
	v_mfma_f32_16x16x32_bf16 v[54:57], v[238:241], v[190:193], v[54:57]
	v_mfma_f32_16x16x32_bf16 v[50:53], v[246:249], v[190:193], v[50:53]
	v_mfma_f32_16x16x32_bf16 v[38:41], v[238:241], v[198:201], v[38:41]
	v_mfma_f32_16x16x32_bf16 v[34:37], v[246:249], v[198:201], v[34:37]
	v_mfma_f32_16x16x32_bf16 v[22:25], v[238:241], v[206:209], v[22:25]
	v_mfma_f32_16x16x32_bf16 v[18:21], v[246:249], v[206:209], v[18:21]
	v_mfma_f32_16x16x32_bf16 v[6:9], v[238:241], v[230:233], v[6:9]
	v_mfma_f32_16x16x32_bf16 v[2:5], v[246:249], v[230:233], v[2:5]
	s_setprio 0
	s_add_i32 s44, s44, 2
	s_add_u32 s28, s28, 0x100
	s_addc_u32 s29, s29, 0
	s_add_u32 s25, s25, 0x100
	s_addc_u32 s34, s34, 0
	s_cmp_gt_u32 s44, 13
	s_barrier
.LBB0_362:
	s_add_u32 s1, s28, 0xfffc0080
	s_addc_u32 s22, s29, -1
	s_add_i32 s23, 0, 0x10000
	v_add_u32_e32 v158, s23, v181
	ds_read_b128 v[130:133], v158
	ds_read_b128 v[134:137], v158 offset:1024
	ds_read_b128 v[154:157], v158 offset:2048
	ds_read_b128 v[186:189], v158 offset:3072
	s_cmp_eq_u32 s44, 12
	s_cselect_b32 s43, s17, s22
	s_cselect_b32 s42, s20, s1
	s_cselect_b32 s31, s9, s34
	s_cselect_b32 s30, s21, s25
	v_lshl_add_u64 v[160:161], s[28:29], 0, v[150:151]
	s_add_i32 m0, s49, 0xc000
	ds_read_b128 v[190:193], v185
	ds_read_b128 v[194:197], v185 offset:1024
	ds_read_b128 v[198:201], v185 offset:2048
	ds_read_b128 v[202:205], v185 offset:3072
	ds_read_b128 v[206:209], v185 offset:4096
	ds_read_b128 v[216:219], v185 offset:5120
	ds_read_b128 v[230:233], v185 offset:6144
	ds_read_b128 v[234:237], v185 offset:7168
	global_load_lds_dwordx4 v[160:161], off
	v_lshl_add_u64 v[160:161], s[28:29], 0, v[152:153]
	s_add_i32 m0, s49, 0xe000
	s_nop 0
	global_load_lds_dwordx4 v[160:161], off
	s_add_i32 s1, 0, 0x14000
	v_add_u32_e32 v158, s1, v181
	ds_read_b128 v[238:241], v158
	ds_read_b128 v[242:245], v158 offset:1024
	ds_read_b128 v[246:249], v158 offset:2048
	ds_read_b128 v[176:179], v158 offset:3072
	s_waitcnt vmcnt(8)
	s_waitcnt lgkmcnt(0)
	s_barrier
	s_setprio 1
	v_mfma_f32_16x16x32_bf16 v[126:129], v[130:133], v[190:193], v[126:129]
	v_mfma_f32_16x16x32_bf16 v[122:125], v[154:157], v[190:193], v[122:125]
	v_mfma_f32_16x16x32_bf16 v[110:113], v[130:133], v[198:201], v[110:113]
	v_mfma_f32_16x16x32_bf16 v[106:109], v[154:157], v[198:201], v[106:109]
	v_mfma_f32_16x16x32_bf16 v[94:97], v[130:133], v[206:209], v[94:97]
	v_mfma_f32_16x16x32_bf16 v[90:93], v[154:157], v[206:209], v[90:93]
	v_mfma_f32_16x16x32_bf16 v[78:81], v[130:133], v[230:233], v[78:81]
	v_mfma_f32_16x16x32_bf16 v[74:77], v[154:157], v[230:233], v[74:77]
	v_mfma_f32_16x16x32_bf16 v[126:129], v[134:137], v[194:197], v[126:129]
	v_mfma_f32_16x16x32_bf16 v[122:125], v[186:189], v[194:197], v[122:125]
	v_mfma_f32_16x16x32_bf16 v[110:113], v[134:137], v[202:205], v[110:113]
	v_mfma_f32_16x16x32_bf16 v[106:109], v[186:189], v[202:205], v[106:109]
	v_mfma_f32_16x16x32_bf16 v[94:97], v[134:137], v[216:219], v[94:97]
	v_mfma_f32_16x16x32_bf16 v[90:93], v[186:189], v[216:219], v[90:93]
	v_mfma_f32_16x16x32_bf16 v[78:81], v[134:137], v[234:237], v[78:81]
	v_mfma_f32_16x16x32_bf16 v[74:77], v[186:189], v[234:237], v[74:77]
	v_mfma_f32_16x16x32_bf16 v[118:121], v[238:241], v[190:193], v[118:121]
	v_mfma_f32_16x16x32_bf16 v[114:117], v[246:249], v[190:193], v[114:117]
	v_mfma_f32_16x16x32_bf16 v[102:105], v[238:241], v[198:201], v[102:105]
	v_mfma_f32_16x16x32_bf16 v[98:101], v[246:249], v[198:201], v[98:101]
	v_mfma_f32_16x16x32_bf16 v[86:89], v[238:241], v[206:209], v[86:89]
	v_mfma_f32_16x16x32_bf16 v[82:85], v[246:249], v[206:209], v[82:85]
	v_mfma_f32_16x16x32_bf16 v[70:73], v[238:241], v[230:233], v[70:73]
	v_mfma_f32_16x16x32_bf16 v[66:69], v[246:249], v[230:233], v[66:69]
	v_mfma_f32_16x16x32_bf16 v[118:121], v[242:245], v[194:197], v[118:121]
	v_mfma_f32_16x16x32_bf16 v[114:117], v[176:179], v[194:197], v[114:117]
	v_mfma_f32_16x16x32_bf16 v[102:105], v[242:245], v[202:205], v[102:105]
	v_mfma_f32_16x16x32_bf16 v[98:101], v[176:179], v[202:205], v[98:101]
	v_mfma_f32_16x16x32_bf16 v[86:89], v[242:245], v[216:219], v[86:89]
	v_mfma_f32_16x16x32_bf16 v[82:85], v[176:179], v[216:219], v[82:85]
	v_mfma_f32_16x16x32_bf16 v[70:73], v[242:245], v[234:237], v[70:73]
	v_mfma_f32_16x16x32_bf16 v[66:69], v[176:179], v[234:237], v[66:69]
	s_setprio 0
	s_barrier
	ds_read_b128 v[190:193], v185 offset:16384
	ds_read_b128 v[194:197], v185 offset:17408
	ds_read_b128 v[198:201], v185 offset:18432
	ds_read_b128 v[202:205], v185 offset:19456
	ds_read_b128 v[206:209], v185 offset:20480
	ds_read_b128 v[216:219], v185 offset:21504
	ds_read_b128 v[230:233], v185 offset:22528
	ds_read_b128 v[234:237], v185 offset:23552
	s_cbranch_vccz .Lss_proj1
	v_lshlrev_b32_e32 v160, 4, v167
	s_lshl_b32 m0, s49, 1
	v_add_u32_e32 v160, s49, v160
	s_add_i32 m0, m0, 0x20000
	s_mov_b64 vcc, 0
	global_load_lds_dwordx4 v160, s[98:99]
	global_load_lds_dwordx4 v160, s[98:99] offset:1024
